# P0 folded pooling weight rewritten: coalesced dwordx4 rows + scalar-loaded pool_w/pool_scale (4x fewer VMEM instructions), on top of attn resched + pooling rewrite + early GEMM barrier
# speedup vs baseline: 1.0282x; 1.0028x over previous
; __device__ __forceinline__ unsigned f2bf(float f) { unsigned u = __builtin_bit_cast(unsigned, f); return (u + 0x7fffu + ((u >> 16) & 1u)) >> 16; }
; __global__ void __launch_bounds__(512, 2) fwd_mega(Args a) {
;     ...
;         { const float* pw = a.in[12]; const float* psc = a.in[13]; const float* wbp = a.in[15];
;           for (int w = gw; w < 1024 * 8; w += NGW) { const int n = w & 1023, gc = (w >> 10) * 64 + lane, g = gc >> 7;
;               float acc = 0.f;
;               for (int d = 0; d < 128; ++d) acc += pw[(size_t)gc * 128 + d] * psc[g * 128 + d] * wbp[(size_t)(g * 128 + d) * 1024 + n];
;               Wba[(size_t)n * 1024 + 512 + gc] = (bf16)f2bf(acc); } }
.LBB0_121:
	s_cmpk_gt_i32 s8, 0x7ff
	s_cbranch_scc1 .LBB0_126
	s_waitcnt lgkmcnt(0)
	s_mov_b64 s[58:59], s[44:45]
	s_mov_b64 s[12:13], s[46:47]
	s_mov_b64 s[64:65], s[50:51]
	v_lshlrev_b32_e32 v6, 4, v203
.Lfold_item:
	s_lshr_b32 s0, s8, 2
	s_and_b32 s1, s8, 3
	s_lshl_b32 s4, s0, 9
	s_add_u32 s98, s58, s4
	s_addc_u32 s99, s59, 0
	s_lshr_b32 s10, s0, 7
	s_lshl_b32 s4, s10, 9
	s_add_u32 s100, s12, s4
	s_addc_u32 s101, s13, 0
	s_lshl_b32 s4, s10, 19
	s_lshl_b32 s5, s1, 10
	s_add_u32 s4, s4, s5
	s_add_u32 s18, s64, s4
	s_addc_u32 s19, s65, 0
	v_mov_b32_e32 v0, 0
	v_mov_b32_e32 v1, 0
	v_mov_b32_e32 v2, 0
	v_mov_b32_e32 v3, 0
	global_load_dwordx4 v[8:11], v6, s[18:19]
	s_add_u32 s4, s18, 0x1000
	s_addc_u32 s5, s19, 0
	global_load_dwordx4 v[12:15], v6, s[4:5]
	s_add_u32 s4, s18, 0x2000
	s_addc_u32 s5, s19, 0
	global_load_dwordx4 v[16:19], v6, s[4:5]
	s_add_u32 s4, s18, 0x3000
	s_addc_u32 s5, s19, 0
	global_load_dwordx4 v[20:23], v6, s[4:5]
	s_add_u32 s4, s18, 0x4000
	s_addc_u32 s5, s19, 0
	global_load_dwordx4 v[24:27], v6, s[4:5]
	s_add_u32 s4, s18, 0x5000
	s_addc_u32 s5, s19, 0
	global_load_dwordx4 v[28:31], v6, s[4:5]
	s_add_u32 s4, s18, 0x6000
	s_addc_u32 s5, s19, 0
	global_load_dwordx4 v[32:35], v6, s[4:5]
	s_add_u32 s4, s18, 0x7000
	s_addc_u32 s5, s19, 0
	global_load_dwordx4 v[36:39], v6, s[4:5]
	s_add_u32 s4, s18, 0x8000
	s_addc_u32 s5, s19, 0
	global_load_dwordx4 v[40:43], v6, s[4:5]
	s_add_u32 s4, s18, 0x9000
	s_addc_u32 s5, s19, 0
	global_load_dwordx4 v[44:47], v6, s[4:5]
	s_add_u32 s4, s18, 0xa000
	s_addc_u32 s5, s19, 0
	global_load_dwordx4 v[48:51], v6, s[4:5]
	s_add_u32 s4, s18, 0xb000
	s_addc_u32 s5, s19, 0
	global_load_dwordx4 v[52:55], v6, s[4:5]
	s_add_u32 s4, s18, 0xc000
	s_addc_u32 s5, s19, 0
	global_load_dwordx4 v[56:59], v6, s[4:5]
	s_add_u32 s4, s18, 0xd000
	s_addc_u32 s5, s19, 0
	global_load_dwordx4 v[60:63], v6, s[4:5]
	s_add_u32 s4, s18, 0xe000
	s_addc_u32 s5, s19, 0
	global_load_dwordx4 v[64:67], v6, s[4:5]
	s_add_u32 s4, s18, 0xf000
	s_addc_u32 s5, s19, 0
	global_load_dwordx4 v[68:71], v6, s[4:5]
	s_add_u32 s4, s18, 0x10000
	s_addc_u32 s5, s19, 0
	global_load_dwordx4 v[72:75], v6, s[4:5]
	s_add_u32 s4, s18, 0x11000
	s_addc_u32 s5, s19, 0
	global_load_dwordx4 v[76:79], v6, s[4:5]
	s_add_u32 s4, s18, 0x12000
	s_addc_u32 s5, s19, 0
	global_load_dwordx4 v[80:83], v6, s[4:5]
	s_add_u32 s4, s18, 0x13000
	s_addc_u32 s5, s19, 0
	global_load_dwordx4 v[84:87], v6, s[4:5]
	s_add_u32 s4, s18, 0x14000
	s_addc_u32 s5, s19, 0
	global_load_dwordx4 v[88:91], v6, s[4:5]
	s_add_u32 s4, s18, 0x15000
	s_addc_u32 s5, s19, 0
	global_load_dwordx4 v[92:95], v6, s[4:5]
	s_add_u32 s4, s18, 0x16000
	s_addc_u32 s5, s19, 0
	global_load_dwordx4 v[96:99], v6, s[4:5]
	s_add_u32 s4, s18, 0x17000
	s_addc_u32 s5, s19, 0
	global_load_dwordx4 v[100:103], v6, s[4:5]
	s_add_u32 s4, s18, 0x18000
	s_addc_u32 s5, s19, 0
	global_load_dwordx4 v[104:107], v6, s[4:5]
	s_add_u32 s4, s18, 0x19000
	s_addc_u32 s5, s19, 0
	global_load_dwordx4 v[108:111], v6, s[4:5]
	s_add_u32 s4, s18, 0x1a000
	s_addc_u32 s5, s19, 0
	global_load_dwordx4 v[112:115], v6, s[4:5]
	s_add_u32 s4, s18, 0x1b000
	s_addc_u32 s5, s19, 0
	global_load_dwordx4 v[116:119], v6, s[4:5]
	s_add_u32 s4, s18, 0x1c000
	s_addc_u32 s5, s19, 0
	global_load_dwordx4 v[120:123], v6, s[4:5]
	s_add_u32 s4, s18, 0x1d000
	s_addc_u32 s5, s19, 0
	global_load_dwordx4 v[124:127], v6, s[4:5]
	s_add_u32 s4, s18, 0x1e000
	s_addc_u32 s5, s19, 0
	global_load_dwordx4 v[128:131], v6, s[4:5]
	s_add_u32 s4, s18, 0x1f000
	s_addc_u32 s5, s19, 0
	global_load_dwordx4 v[132:135], v6, s[4:5]
	s_load_dwordx8 s[44:51], s[98:99], 0x0
	s_load_dwordx4 s[60:63], s[100:101], 0x0
	s_load_dwordx4 s[20:23], s[100:101], 0x10
	s_waitcnt vmcnt(0) lgkmcnt(0)
	v_mov_b32_e32 v4, s60
	v_mul_f32_e32 v4, s44, v4
	v_fmac_f32_e32 v0, v4, v8
	v_fmac_f32_e32 v1, v4, v9
	v_fmac_f32_e32 v2, v4, v10
	v_fmac_f32_e32 v3, v4, v11
	v_mov_b32_e32 v4, s61
	v_mul_f32_e32 v4, s45, v4
	v_fmac_f32_e32 v0, v4, v12
	v_fmac_f32_e32 v1, v4, v13
	v_fmac_f32_e32 v2, v4, v14
	v_fmac_f32_e32 v3, v4, v15
	v_mov_b32_e32 v4, s62
	v_mul_f32_e32 v4, s46, v4
	v_fmac_f32_e32 v0, v4, v16
	v_fmac_f32_e32 v1, v4, v17
	v_fmac_f32_e32 v2, v4, v18
	v_fmac_f32_e32 v3, v4, v19
	v_mov_b32_e32 v4, s63
	v_mul_f32_e32 v4, s47, v4
	v_fmac_f32_e32 v0, v4, v20
	v_fmac_f32_e32 v1, v4, v21
	v_fmac_f32_e32 v2, v4, v22
	v_fmac_f32_e32 v3, v4, v23
	v_mov_b32_e32 v4, s20
	v_mul_f32_e32 v4, s48, v4
	v_fmac_f32_e32 v0, v4, v24
	v_fmac_f32_e32 v1, v4, v25
	v_fmac_f32_e32 v2, v4, v26
	v_fmac_f32_e32 v3, v4, v27
	v_mov_b32_e32 v4, s21
	v_mul_f32_e32 v4, s49, v4
	v_fmac_f32_e32 v0, v4, v28
	v_fmac_f32_e32 v1, v4, v29
	v_fmac_f32_e32 v2, v4, v30
	v_fmac_f32_e32 v3, v4, v31
	v_mov_b32_e32 v4, s22
	v_mul_f32_e32 v4, s50, v4
	v_fmac_f32_e32 v0, v4, v32
	v_fmac_f32_e32 v1, v4, v33
	v_fmac_f32_e32 v2, v4, v34
	v_fmac_f32_e32 v3, v4, v35
	v_mov_b32_e32 v4, s23
	v_mul_f32_e32 v4, s51, v4
	v_fmac_f32_e32 v0, v4, v36
	v_fmac_f32_e32 v1, v4, v37
	v_fmac_f32_e32 v2, v4, v38
	v_fmac_f32_e32 v3, v4, v39
	s_load_dwordx8 s[44:51], s[98:99], 0x20
	s_load_dwordx4 s[60:63], s[100:101], 0x20
	s_load_dwordx4 s[20:23], s[100:101], 0x30
	s_waitcnt lgkmcnt(0)
; __global__ void __launch_bounds__(512, 2) fwd_mega(Args a) {
;     ...
;           for (int w = gw; w < 1024 * 8; w += NGW) { const int n = w & 1023, gc = (w >> 10) * 64 + lane, g = gc >> 7;
;               float acc = 0.f;
;               for (int d = 0; d < 128; ++d) acc += pw[(size_t)gc * 128 + d] * psc[g * 128 + d] * wbp[(size_t)(g * 128 + d) * 1024 + n];
	v_mov_b32_e32 v4, s60
	v_mul_f32_e32 v4, s44, v4
	v_fmac_f32_e32 v0, v4, v40
	v_fmac_f32_e32 v1, v4, v41
	v_fmac_f32_e32 v2, v4, v42
	v_fmac_f32_e32 v3, v4, v43
	v_mov_b32_e32 v4, s61
	v_mul_f32_e32 v4, s45, v4
	v_fmac_f32_e32 v0, v4, v44
	v_fmac_f32_e32 v1, v4, v45
	v_fmac_f32_e32 v2, v4, v46
	v_fmac_f32_e32 v3, v4, v47
	v_mov_b32_e32 v4, s62
	v_mul_f32_e32 v4, s46, v4
	v_fmac_f32_e32 v0, v4, v48
	v_fmac_f32_e32 v1, v4, v49
	v_fmac_f32_e32 v2, v4, v50
	v_fmac_f32_e32 v3, v4, v51
	v_mov_b32_e32 v4, s63
	v_mul_f32_e32 v4, s47, v4
	v_fmac_f32_e32 v0, v4, v52
	v_fmac_f32_e32 v1, v4, v53
	v_fmac_f32_e32 v2, v4, v54
	v_fmac_f32_e32 v3, v4, v55
	v_mov_b32_e32 v4, s20
	v_mul_f32_e32 v4, s48, v4
	v_fmac_f32_e32 v0, v4, v56
	v_fmac_f32_e32 v1, v4, v57
	v_fmac_f32_e32 v2, v4, v58
	v_fmac_f32_e32 v3, v4, v59
	v_mov_b32_e32 v4, s21
	v_mul_f32_e32 v4, s49, v4
	v_fmac_f32_e32 v0, v4, v60
	v_fmac_f32_e32 v1, v4, v61
	v_fmac_f32_e32 v2, v4, v62
	v_fmac_f32_e32 v3, v4, v63
	v_mov_b32_e32 v4, s22
	v_mul_f32_e32 v4, s50, v4
	v_fmac_f32_e32 v0, v4, v64
	v_fmac_f32_e32 v1, v4, v65
	v_fmac_f32_e32 v2, v4, v66
	v_fmac_f32_e32 v3, v4, v67
	v_mov_b32_e32 v4, s23
	v_mul_f32_e32 v4, s51, v4
	v_fmac_f32_e32 v0, v4, v68
	v_fmac_f32_e32 v1, v4, v69
	v_fmac_f32_e32 v2, v4, v70
	v_fmac_f32_e32 v3, v4, v71
	s_load_dwordx8 s[44:51], s[98:99], 0x40
	s_load_dwordx4 s[60:63], s[100:101], 0x40
	s_load_dwordx4 s[20:23], s[100:101], 0x50
	s_waitcnt lgkmcnt(0)
	v_mov_b32_e32 v4, s60
	v_mul_f32_e32 v4, s44, v4
	v_fmac_f32_e32 v0, v4, v72
	v_fmac_f32_e32 v1, v4, v73
	v_fmac_f32_e32 v2, v4, v74
	v_fmac_f32_e32 v3, v4, v75
	v_mov_b32_e32 v4, s61
	v_mul_f32_e32 v4, s45, v4
	v_fmac_f32_e32 v0, v4, v76
	v_fmac_f32_e32 v1, v4, v77
	v_fmac_f32_e32 v2, v4, v78
	v_fmac_f32_e32 v3, v4, v79
	v_mov_b32_e32 v4, s62
	v_mul_f32_e32 v4, s46, v4
	v_fmac_f32_e32 v0, v4, v80
	v_fmac_f32_e32 v1, v4, v81
	v_fmac_f32_e32 v2, v4, v82
	v_fmac_f32_e32 v3, v4, v83
	v_mov_b32_e32 v4, s63
	v_mul_f32_e32 v4, s47, v4
	v_fmac_f32_e32 v0, v4, v84
	v_fmac_f32_e32 v1, v4, v85
	v_fmac_f32_e32 v2, v4, v86
	v_fmac_f32_e32 v3, v4, v87
	v_mov_b32_e32 v4, s20
	v_mul_f32_e32 v4, s48, v4
	v_fmac_f32_e32 v0, v4, v88
	v_fmac_f32_e32 v1, v4, v89
	v_fmac_f32_e32 v2, v4, v90
	v_fmac_f32_e32 v3, v4, v91
	v_mov_b32_e32 v4, s21
	v_mul_f32_e32 v4, s49, v4
	v_fmac_f32_e32 v0, v4, v92
	v_fmac_f32_e32 v1, v4, v93
	v_fmac_f32_e32 v2, v4, v94
	v_fmac_f32_e32 v3, v4, v95
	v_mov_b32_e32 v4, s22
	v_mul_f32_e32 v4, s50, v4
	v_fmac_f32_e32 v0, v4, v96
	v_fmac_f32_e32 v1, v4, v97
	v_fmac_f32_e32 v2, v4, v98
	v_fmac_f32_e32 v3, v4, v99
	v_mov_b32_e32 v4, s23
	v_mul_f32_e32 v4, s51, v4
	v_fmac_f32_e32 v0, v4, v100
	v_fmac_f32_e32 v1, v4, v101
	v_fmac_f32_e32 v2, v4, v102
	v_fmac_f32_e32 v3, v4, v103
	s_load_dwordx8 s[44:51], s[98:99], 0x60
	s_load_dwordx4 s[60:63], s[100:101], 0x60
	s_load_dwordx4 s[20:23], s[100:101], 0x70
	s_waitcnt lgkmcnt(0)
	v_mov_b32_e32 v4, s60
	v_mul_f32_e32 v4, s44, v4
	v_fmac_f32_e32 v0, v4, v104
	v_fmac_f32_e32 v1, v4, v105
	v_fmac_f32_e32 v2, v4, v106
	v_fmac_f32_e32 v3, v4, v107
	v_mov_b32_e32 v4, s61
	v_mul_f32_e32 v4, s45, v4
	v_fmac_f32_e32 v0, v4, v108
	v_fmac_f32_e32 v1, v4, v109
	v_fmac_f32_e32 v2, v4, v110
	v_fmac_f32_e32 v3, v4, v111
	v_mov_b32_e32 v4, s62
	v_mul_f32_e32 v4, s46, v4
	v_fmac_f32_e32 v0, v4, v112
	v_fmac_f32_e32 v1, v4, v113
	v_fmac_f32_e32 v2, v4, v114
	v_fmac_f32_e32 v3, v4, v115
	v_mov_b32_e32 v4, s63
	v_mul_f32_e32 v4, s47, v4
	v_fmac_f32_e32 v0, v4, v116
	v_fmac_f32_e32 v1, v4, v117
	v_fmac_f32_e32 v2, v4, v118
	v_fmac_f32_e32 v3, v4, v119
	v_mov_b32_e32 v4, s20
	v_mul_f32_e32 v4, s48, v4
	v_fmac_f32_e32 v0, v4, v120
	v_fmac_f32_e32 v1, v4, v121
	v_fmac_f32_e32 v2, v4, v122
	v_fmac_f32_e32 v3, v4, v123
	v_mov_b32_e32 v4, s21
	v_mul_f32_e32 v4, s49, v4
	v_fmac_f32_e32 v0, v4, v124
	v_fmac_f32_e32 v1, v4, v125
	v_fmac_f32_e32 v2, v4, v126
	v_fmac_f32_e32 v3, v4, v127
	v_mov_b32_e32 v4, s22
	v_mul_f32_e32 v4, s50, v4
	v_fmac_f32_e32 v0, v4, v128
	v_fmac_f32_e32 v1, v4, v129
	v_fmac_f32_e32 v2, v4, v130
	v_fmac_f32_e32 v3, v4, v131
	v_mov_b32_e32 v4, s23
	v_mul_f32_e32 v4, s51, v4
	v_fmac_f32_e32 v0, v4, v132
	v_fmac_f32_e32 v1, v4, v133
	v_fmac_f32_e32 v2, v4, v134
	v_fmac_f32_e32 v3, v4, v135
	s_add_u32 s4, s18, 0x20000
	s_addc_u32 s5, s19, 0
	global_load_dwordx4 v[8:11], v6, s[4:5]
	s_add_u32 s4, s18, 0x21000
	s_addc_u32 s5, s19, 0
	global_load_dwordx4 v[12:15], v6, s[4:5]
	s_add_u32 s4, s18, 0x22000
	s_addc_u32 s5, s19, 0
	global_load_dwordx4 v[16:19], v6, s[4:5]
	s_add_u32 s4, s18, 0x23000
	s_addc_u32 s5, s19, 0
	global_load_dwordx4 v[20:23], v6, s[4:5]
	s_add_u32 s4, s18, 0x24000
	s_addc_u32 s5, s19, 0
	global_load_dwordx4 v[24:27], v6, s[4:5]
	s_add_u32 s4, s18, 0x25000
	s_addc_u32 s5, s19, 0
	global_load_dwordx4 v[28:31], v6, s[4:5]
	s_add_u32 s4, s18, 0x26000
	s_addc_u32 s5, s19, 0
	global_load_dwordx4 v[32:35], v6, s[4:5]
	s_add_u32 s4, s18, 0x27000
	s_addc_u32 s5, s19, 0
	global_load_dwordx4 v[36:39], v6, s[4:5]
	s_add_u32 s4, s18, 0x28000
	s_addc_u32 s5, s19, 0
	global_load_dwordx4 v[40:43], v6, s[4:5]
	s_add_u32 s4, s18, 0x29000
	s_addc_u32 s5, s19, 0
	global_load_dwordx4 v[44:47], v6, s[4:5]
	s_add_u32 s4, s18, 0x2a000
	s_addc_u32 s5, s19, 0
	global_load_dwordx4 v[48:51], v6, s[4:5]
	s_add_u32 s4, s18, 0x2b000
	s_addc_u32 s5, s19, 0
	global_load_dwordx4 v[52:55], v6, s[4:5]
	s_add_u32 s4, s18, 0x2c000
	s_addc_u32 s5, s19, 0
	global_load_dwordx4 v[56:59], v6, s[4:5]
	s_add_u32 s4, s18, 0x2d000
	s_addc_u32 s5, s19, 0
	global_load_dwordx4 v[60:63], v6, s[4:5]
	s_add_u32 s4, s18, 0x2e000
	s_addc_u32 s5, s19, 0
	global_load_dwordx4 v[64:67], v6, s[4:5]
	s_add_u32 s4, s18, 0x2f000
; __global__ void __launch_bounds__(512, 2) fwd_mega(Args a) {
;     ...
;           for (int w = gw; w < 1024 * 8; w += NGW) { const int n = w & 1023, gc = (w >> 10) * 64 + lane, g = gc >> 7;
;               float acc = 0.f;
;               for (int d = 0; d < 128; ++d) acc += pw[(size_t)gc * 128 + d] * psc[g * 128 + d] * wbp[(size_t)(g * 128 + d) * 1024 + n];
	s_addc_u32 s5, s19, 0
	global_load_dwordx4 v[68:71], v6, s[4:5]
	s_add_u32 s4, s18, 0x30000
	s_addc_u32 s5, s19, 0
	global_load_dwordx4 v[72:75], v6, s[4:5]
	s_add_u32 s4, s18, 0x31000
	s_addc_u32 s5, s19, 0
	global_load_dwordx4 v[76:79], v6, s[4:5]
	s_add_u32 s4, s18, 0x32000
	s_addc_u32 s5, s19, 0
	global_load_dwordx4 v[80:83], v6, s[4:5]
	s_add_u32 s4, s18, 0x33000
	s_addc_u32 s5, s19, 0
	global_load_dwordx4 v[84:87], v6, s[4:5]
	s_add_u32 s4, s18, 0x34000
	s_addc_u32 s5, s19, 0
	global_load_dwordx4 v[88:91], v6, s[4:5]
	s_add_u32 s4, s18, 0x35000
	s_addc_u32 s5, s19, 0
	global_load_dwordx4 v[92:95], v6, s[4:5]
	s_add_u32 s4, s18, 0x36000
	s_addc_u32 s5, s19, 0
	global_load_dwordx4 v[96:99], v6, s[4:5]
	s_add_u32 s4, s18, 0x37000
	s_addc_u32 s5, s19, 0
	global_load_dwordx4 v[100:103], v6, s[4:5]
	s_add_u32 s4, s18, 0x38000
	s_addc_u32 s5, s19, 0
	global_load_dwordx4 v[104:107], v6, s[4:5]
	s_add_u32 s4, s18, 0x39000
	s_addc_u32 s5, s19, 0
	global_load_dwordx4 v[108:111], v6, s[4:5]
	s_add_u32 s4, s18, 0x3a000
	s_addc_u32 s5, s19, 0
	global_load_dwordx4 v[112:115], v6, s[4:5]
	s_add_u32 s4, s18, 0x3b000
	s_addc_u32 s5, s19, 0
	global_load_dwordx4 v[116:119], v6, s[4:5]
	s_add_u32 s4, s18, 0x3c000
	s_addc_u32 s5, s19, 0
	global_load_dwordx4 v[120:123], v6, s[4:5]
	s_add_u32 s4, s18, 0x3d000
	s_addc_u32 s5, s19, 0
	global_load_dwordx4 v[124:127], v6, s[4:5]
	s_add_u32 s4, s18, 0x3e000
	s_addc_u32 s5, s19, 0
	global_load_dwordx4 v[128:131], v6, s[4:5]
	s_add_u32 s4, s18, 0x3f000
	s_addc_u32 s5, s19, 0
	global_load_dwordx4 v[132:135], v6, s[4:5]
	s_load_dwordx8 s[44:51], s[98:99], 0x80
	s_load_dwordx4 s[60:63], s[100:101], 0x80
	s_load_dwordx4 s[20:23], s[100:101], 0x90
	s_waitcnt vmcnt(0) lgkmcnt(0)
	v_mov_b32_e32 v4, s60
	v_mul_f32_e32 v4, s44, v4
	v_fmac_f32_e32 v0, v4, v8
	v_fmac_f32_e32 v1, v4, v9
	v_fmac_f32_e32 v2, v4, v10
	v_fmac_f32_e32 v3, v4, v11
	v_mov_b32_e32 v4, s61
	v_mul_f32_e32 v4, s45, v4
	v_fmac_f32_e32 v0, v4, v12
	v_fmac_f32_e32 v1, v4, v13
	v_fmac_f32_e32 v2, v4, v14
	v_fmac_f32_e32 v3, v4, v15
	v_mov_b32_e32 v4, s62
	v_mul_f32_e32 v4, s46, v4
	v_fmac_f32_e32 v0, v4, v16
	v_fmac_f32_e32 v1, v4, v17
	v_fmac_f32_e32 v2, v4, v18
	v_fmac_f32_e32 v3, v4, v19
	v_mov_b32_e32 v4, s63
	v_mul_f32_e32 v4, s47, v4
	v_fmac_f32_e32 v0, v4, v20
	v_fmac_f32_e32 v1, v4, v21
	v_fmac_f32_e32 v2, v4, v22
	v_fmac_f32_e32 v3, v4, v23
	v_mov_b32_e32 v4, s20
	v_mul_f32_e32 v4, s48, v4
	v_fmac_f32_e32 v0, v4, v24
	v_fmac_f32_e32 v1, v4, v25
	v_fmac_f32_e32 v2, v4, v26
	v_fmac_f32_e32 v3, v4, v27
	v_mov_b32_e32 v4, s21
	v_mul_f32_e32 v4, s49, v4
	v_fmac_f32_e32 v0, v4, v28
	v_fmac_f32_e32 v1, v4, v29
	v_fmac_f32_e32 v2, v4, v30
	v_fmac_f32_e32 v3, v4, v31
	v_mov_b32_e32 v4, s22
	v_mul_f32_e32 v4, s50, v4
	v_fmac_f32_e32 v0, v4, v32
	v_fmac_f32_e32 v1, v4, v33
	v_fmac_f32_e32 v2, v4, v34
	v_fmac_f32_e32 v3, v4, v35
	v_mov_b32_e32 v4, s23
	v_mul_f32_e32 v4, s51, v4
	v_fmac_f32_e32 v0, v4, v36
	v_fmac_f32_e32 v1, v4, v37
	v_fmac_f32_e32 v2, v4, v38
	v_fmac_f32_e32 v3, v4, v39
	s_load_dwordx8 s[44:51], s[98:99], 0xa0
	s_load_dwordx4 s[60:63], s[100:101], 0xa0
	s_load_dwordx4 s[20:23], s[100:101], 0xb0
	s_waitcnt lgkmcnt(0)
	v_mov_b32_e32 v4, s60
	v_mul_f32_e32 v4, s44, v4
	v_fmac_f32_e32 v0, v4, v40
	v_fmac_f32_e32 v1, v4, v41
	v_fmac_f32_e32 v2, v4, v42
	v_fmac_f32_e32 v3, v4, v43
	v_mov_b32_e32 v4, s61
	v_mul_f32_e32 v4, s45, v4
	v_fmac_f32_e32 v0, v4, v44
	v_fmac_f32_e32 v1, v4, v45
	v_fmac_f32_e32 v2, v4, v46
	v_fmac_f32_e32 v3, v4, v47
	v_mov_b32_e32 v4, s62
	v_mul_f32_e32 v4, s46, v4
	v_fmac_f32_e32 v0, v4, v48
	v_fmac_f32_e32 v1, v4, v49
	v_fmac_f32_e32 v2, v4, v50
	v_fmac_f32_e32 v3, v4, v51
	v_mov_b32_e32 v4, s63
	v_mul_f32_e32 v4, s47, v4
	v_fmac_f32_e32 v0, v4, v52
	v_fmac_f32_e32 v1, v4, v53
	v_fmac_f32_e32 v2, v4, v54
	v_fmac_f32_e32 v3, v4, v55
	v_mov_b32_e32 v4, s20
	v_mul_f32_e32 v4, s48, v4
	v_fmac_f32_e32 v0, v4, v56
	v_fmac_f32_e32 v1, v4, v57
	v_fmac_f32_e32 v2, v4, v58
	v_fmac_f32_e32 v3, v4, v59
	v_mov_b32_e32 v4, s21
	v_mul_f32_e32 v4, s49, v4
	v_fmac_f32_e32 v0, v4, v60
	v_fmac_f32_e32 v1, v4, v61
	v_fmac_f32_e32 v2, v4, v62
	v_fmac_f32_e32 v3, v4, v63
	v_mov_b32_e32 v4, s22
	v_mul_f32_e32 v4, s50, v4
	v_fmac_f32_e32 v0, v4, v64
	v_fmac_f32_e32 v1, v4, v65
	v_fmac_f32_e32 v2, v4, v66
	v_fmac_f32_e32 v3, v4, v67
	v_mov_b32_e32 v4, s23
	v_mul_f32_e32 v4, s51, v4
	v_fmac_f32_e32 v0, v4, v68
	v_fmac_f32_e32 v1, v4, v69
	v_fmac_f32_e32 v2, v4, v70
	v_fmac_f32_e32 v3, v4, v71
	s_load_dwordx8 s[44:51], s[98:99], 0xc0
	s_load_dwordx4 s[60:63], s[100:101], 0xc0
	s_load_dwordx4 s[20:23], s[100:101], 0xd0
	s_waitcnt lgkmcnt(0)
	v_mov_b32_e32 v4, s60
	v_mul_f32_e32 v4, s44, v4
	v_fmac_f32_e32 v0, v4, v72
	v_fmac_f32_e32 v1, v4, v73
	v_fmac_f32_e32 v2, v4, v74
	v_fmac_f32_e32 v3, v4, v75
	v_mov_b32_e32 v4, s61
	v_mul_f32_e32 v4, s45, v4
	v_fmac_f32_e32 v0, v4, v76
	v_fmac_f32_e32 v1, v4, v77
	v_fmac_f32_e32 v2, v4, v78
	v_fmac_f32_e32 v3, v4, v79
	v_mov_b32_e32 v4, s62
	v_mul_f32_e32 v4, s46, v4
	v_fmac_f32_e32 v0, v4, v80
	v_fmac_f32_e32 v1, v4, v81
	v_fmac_f32_e32 v2, v4, v82
	v_fmac_f32_e32 v3, v4, v83
	v_mov_b32_e32 v4, s63
	v_mul_f32_e32 v4, s47, v4
	v_fmac_f32_e32 v0, v4, v84
	v_fmac_f32_e32 v1, v4, v85
	v_fmac_f32_e32 v2, v4, v86
	v_fmac_f32_e32 v3, v4, v87
	v_mov_b32_e32 v4, s20
	v_mul_f32_e32 v4, s48, v4
	v_fmac_f32_e32 v0, v4, v88
	v_fmac_f32_e32 v1, v4, v89
	v_fmac_f32_e32 v2, v4, v90
	v_fmac_f32_e32 v3, v4, v91
	v_mov_b32_e32 v4, s21
	v_mul_f32_e32 v4, s49, v4
	v_fmac_f32_e32 v0, v4, v92
	v_fmac_f32_e32 v1, v4, v93
	v_fmac_f32_e32 v2, v4, v94
	v_fmac_f32_e32 v3, v4, v95
	v_mov_b32_e32 v4, s22
	v_mul_f32_e32 v4, s50, v4
	v_fmac_f32_e32 v0, v4, v96
	v_fmac_f32_e32 v1, v4, v97
	v_fmac_f32_e32 v2, v4, v98
	v_fmac_f32_e32 v3, v4, v99
	v_mov_b32_e32 v4, s23
	v_mul_f32_e32 v4, s51, v4
	v_fmac_f32_e32 v0, v4, v100
	v_fmac_f32_e32 v1, v4, v101
	v_fmac_f32_e32 v2, v4, v102
	v_fmac_f32_e32 v3, v4, v103
	s_load_dwordx8 s[44:51], s[98:99], 0xe0
	s_load_dwordx4 s[60:63], s[100:101], 0xe0
	s_load_dwordx4 s[20:23], s[100:101], 0xf0
	s_waitcnt lgkmcnt(0)
; __global__ void __launch_bounds__(512, 2) fwd_mega(Args a) {
;     ...
;           for (int w = gw; w < 1024 * 8; w += NGW) { const int n = w & 1023, gc = (w >> 10) * 64 + lane, g = gc >> 7;
;               float acc = 0.f;
;               for (int d = 0; d < 128; ++d) acc += pw[(size_t)gc * 128 + d] * psc[g * 128 + d] * wbp[(size_t)(g * 128 + d) * 1024 + n];
	v_mov_b32_e32 v4, s60
	v_mul_f32_e32 v4, s44, v4
	v_fmac_f32_e32 v0, v4, v104
	v_fmac_f32_e32 v1, v4, v105
	v_fmac_f32_e32 v2, v4, v106
	v_fmac_f32_e32 v3, v4, v107
	v_mov_b32_e32 v4, s61
	v_mul_f32_e32 v4, s45, v4
	v_fmac_f32_e32 v0, v4, v108
	v_fmac_f32_e32 v1, v4, v109
	v_fmac_f32_e32 v2, v4, v110
	v_fmac_f32_e32 v3, v4, v111
	v_mov_b32_e32 v4, s62
	v_mul_f32_e32 v4, s46, v4
	v_fmac_f32_e32 v0, v4, v112
	v_fmac_f32_e32 v1, v4, v113
	v_fmac_f32_e32 v2, v4, v114
	v_fmac_f32_e32 v3, v4, v115
	v_mov_b32_e32 v4, s63
	v_mul_f32_e32 v4, s47, v4
	v_fmac_f32_e32 v0, v4, v116
	v_fmac_f32_e32 v1, v4, v117
	v_fmac_f32_e32 v2, v4, v118
	v_fmac_f32_e32 v3, v4, v119
	v_mov_b32_e32 v4, s20
	v_mul_f32_e32 v4, s48, v4
	v_fmac_f32_e32 v0, v4, v120
	v_fmac_f32_e32 v1, v4, v121
	v_fmac_f32_e32 v2, v4, v122
	v_fmac_f32_e32 v3, v4, v123
	v_mov_b32_e32 v4, s21
	v_mul_f32_e32 v4, s49, v4
	v_fmac_f32_e32 v0, v4, v124
	v_fmac_f32_e32 v1, v4, v125
	v_fmac_f32_e32 v2, v4, v126
	v_fmac_f32_e32 v3, v4, v127
	v_mov_b32_e32 v4, s22
	v_mul_f32_e32 v4, s50, v4
	v_fmac_f32_e32 v0, v4, v128
	v_fmac_f32_e32 v1, v4, v129
	v_fmac_f32_e32 v2, v4, v130
	v_fmac_f32_e32 v3, v4, v131
	v_mov_b32_e32 v4, s23
	v_mul_f32_e32 v4, s51, v4
	v_fmac_f32_e32 v0, v4, v132
	v_fmac_f32_e32 v1, v4, v133
	v_fmac_f32_e32 v2, v4, v134
	v_fmac_f32_e32 v3, v4, v135
	s_add_u32 s4, s18, 0x40000
	s_addc_u32 s5, s19, 0
	global_load_dwordx4 v[8:11], v6, s[4:5]
	s_add_u32 s4, s18, 0x41000
	s_addc_u32 s5, s19, 0
	global_load_dwordx4 v[12:15], v6, s[4:5]
	s_add_u32 s4, s18, 0x42000
	s_addc_u32 s5, s19, 0
	global_load_dwordx4 v[16:19], v6, s[4:5]
	s_add_u32 s4, s18, 0x43000
	s_addc_u32 s5, s19, 0
	global_load_dwordx4 v[20:23], v6, s[4:5]
	s_add_u32 s4, s18, 0x44000
	s_addc_u32 s5, s19, 0
	global_load_dwordx4 v[24:27], v6, s[4:5]
	s_add_u32 s4, s18, 0x45000
	s_addc_u32 s5, s19, 0
	global_load_dwordx4 v[28:31], v6, s[4:5]
	s_add_u32 s4, s18, 0x46000
	s_addc_u32 s5, s19, 0
	global_load_dwordx4 v[32:35], v6, s[4:5]
	s_add_u32 s4, s18, 0x47000
	s_addc_u32 s5, s19, 0
	global_load_dwordx4 v[36:39], v6, s[4:5]
	s_add_u32 s4, s18, 0x48000
	s_addc_u32 s5, s19, 0
	global_load_dwordx4 v[40:43], v6, s[4:5]
	s_add_u32 s4, s18, 0x49000
	s_addc_u32 s5, s19, 0
	global_load_dwordx4 v[44:47], v6, s[4:5]
	s_add_u32 s4, s18, 0x4a000
	s_addc_u32 s5, s19, 0
	global_load_dwordx4 v[48:51], v6, s[4:5]
	s_add_u32 s4, s18, 0x4b000
	s_addc_u32 s5, s19, 0
	global_load_dwordx4 v[52:55], v6, s[4:5]
	s_add_u32 s4, s18, 0x4c000
	s_addc_u32 s5, s19, 0
	global_load_dwordx4 v[56:59], v6, s[4:5]
	s_add_u32 s4, s18, 0x4d000
	s_addc_u32 s5, s19, 0
	global_load_dwordx4 v[60:63], v6, s[4:5]
	s_add_u32 s4, s18, 0x4e000
	s_addc_u32 s5, s19, 0
	global_load_dwordx4 v[64:67], v6, s[4:5]
	s_add_u32 s4, s18, 0x4f000
	s_addc_u32 s5, s19, 0
	global_load_dwordx4 v[68:71], v6, s[4:5]
	s_add_u32 s4, s18, 0x50000
	s_addc_u32 s5, s19, 0
	global_load_dwordx4 v[72:75], v6, s[4:5]
	s_add_u32 s4, s18, 0x51000
	s_addc_u32 s5, s19, 0
	global_load_dwordx4 v[76:79], v6, s[4:5]
	s_add_u32 s4, s18, 0x52000
	s_addc_u32 s5, s19, 0
	global_load_dwordx4 v[80:83], v6, s[4:5]
	s_add_u32 s4, s18, 0x53000
	s_addc_u32 s5, s19, 0
	global_load_dwordx4 v[84:87], v6, s[4:5]
	s_add_u32 s4, s18, 0x54000
	s_addc_u32 s5, s19, 0
	global_load_dwordx4 v[88:91], v6, s[4:5]
	s_add_u32 s4, s18, 0x55000
	s_addc_u32 s5, s19, 0
	global_load_dwordx4 v[92:95], v6, s[4:5]
	s_add_u32 s4, s18, 0x56000
	s_addc_u32 s5, s19, 0
	global_load_dwordx4 v[96:99], v6, s[4:5]
	s_add_u32 s4, s18, 0x57000
	s_addc_u32 s5, s19, 0
	global_load_dwordx4 v[100:103], v6, s[4:5]
	s_add_u32 s4, s18, 0x58000
	s_addc_u32 s5, s19, 0
	global_load_dwordx4 v[104:107], v6, s[4:5]
	s_add_u32 s4, s18, 0x59000
	s_addc_u32 s5, s19, 0
	global_load_dwordx4 v[108:111], v6, s[4:5]
	s_add_u32 s4, s18, 0x5a000
	s_addc_u32 s5, s19, 0
	global_load_dwordx4 v[112:115], v6, s[4:5]
	s_add_u32 s4, s18, 0x5b000
	s_addc_u32 s5, s19, 0
	global_load_dwordx4 v[116:119], v6, s[4:5]
	s_add_u32 s4, s18, 0x5c000
	s_addc_u32 s5, s19, 0
	global_load_dwordx4 v[120:123], v6, s[4:5]
	s_add_u32 s4, s18, 0x5d000
	s_addc_u32 s5, s19, 0
	global_load_dwordx4 v[124:127], v6, s[4:5]
	s_add_u32 s4, s18, 0x5e000
	s_addc_u32 s5, s19, 0
	global_load_dwordx4 v[128:131], v6, s[4:5]
	s_add_u32 s4, s18, 0x5f000
	s_addc_u32 s5, s19, 0
	global_load_dwordx4 v[132:135], v6, s[4:5]
	s_load_dwordx8 s[44:51], s[98:99], 0x100
	s_load_dwordx4 s[60:63], s[100:101], 0x100
	s_load_dwordx4 s[20:23], s[100:101], 0x110
	s_waitcnt vmcnt(0) lgkmcnt(0)
	v_mov_b32_e32 v4, s60
	v_mul_f32_e32 v4, s44, v4
	v_fmac_f32_e32 v0, v4, v8
	v_fmac_f32_e32 v1, v4, v9
	v_fmac_f32_e32 v2, v4, v10
	v_fmac_f32_e32 v3, v4, v11
	v_mov_b32_e32 v4, s61
	v_mul_f32_e32 v4, s45, v4
	v_fmac_f32_e32 v0, v4, v12
	v_fmac_f32_e32 v1, v4, v13
	v_fmac_f32_e32 v2, v4, v14
	v_fmac_f32_e32 v3, v4, v15
	v_mov_b32_e32 v4, s62
	v_mul_f32_e32 v4, s46, v4
	v_fmac_f32_e32 v0, v4, v16
	v_fmac_f32_e32 v1, v4, v17
	v_fmac_f32_e32 v2, v4, v18
	v_fmac_f32_e32 v3, v4, v19
	v_mov_b32_e32 v4, s63
	v_mul_f32_e32 v4, s47, v4
	v_fmac_f32_e32 v0, v4, v20
	v_fmac_f32_e32 v1, v4, v21
	v_fmac_f32_e32 v2, v4, v22
	v_fmac_f32_e32 v3, v4, v23
	v_mov_b32_e32 v4, s20
	v_mul_f32_e32 v4, s48, v4
	v_fmac_f32_e32 v0, v4, v24
	v_fmac_f32_e32 v1, v4, v25
	v_fmac_f32_e32 v2, v4, v26
	v_fmac_f32_e32 v3, v4, v27
	v_mov_b32_e32 v4, s21
	v_mul_f32_e32 v4, s49, v4
	v_fmac_f32_e32 v0, v4, v28
	v_fmac_f32_e32 v1, v4, v29
	v_fmac_f32_e32 v2, v4, v30
	v_fmac_f32_e32 v3, v4, v31
	v_mov_b32_e32 v4, s22
	v_mul_f32_e32 v4, s50, v4
	v_fmac_f32_e32 v0, v4, v32
	v_fmac_f32_e32 v1, v4, v33
	v_fmac_f32_e32 v2, v4, v34
	v_fmac_f32_e32 v3, v4, v35
	v_mov_b32_e32 v4, s23
	v_mul_f32_e32 v4, s51, v4
	v_fmac_f32_e32 v0, v4, v36
	v_fmac_f32_e32 v1, v4, v37
	v_fmac_f32_e32 v2, v4, v38
	v_fmac_f32_e32 v3, v4, v39
	s_load_dwordx8 s[44:51], s[98:99], 0x120
	s_load_dwordx4 s[60:63], s[100:101], 0x120
	s_load_dwordx4 s[20:23], s[100:101], 0x130
	s_waitcnt lgkmcnt(0)
; __global__ void __launch_bounds__(512, 2) fwd_mega(Args a) {
;     ...
;           for (int w = gw; w < 1024 * 8; w += NGW) { const int n = w & 1023, gc = (w >> 10) * 64 + lane, g = gc >> 7;
;               float acc = 0.f;
;               for (int d = 0; d < 128; ++d) acc += pw[(size_t)gc * 128 + d] * psc[g * 128 + d] * wbp[(size_t)(g * 128 + d) * 1024 + n];
	v_mov_b32_e32 v4, s60
	v_mul_f32_e32 v4, s44, v4
	v_fmac_f32_e32 v0, v4, v40
	v_fmac_f32_e32 v1, v4, v41
	v_fmac_f32_e32 v2, v4, v42
	v_fmac_f32_e32 v3, v4, v43
	v_mov_b32_e32 v4, s61
	v_mul_f32_e32 v4, s45, v4
	v_fmac_f32_e32 v0, v4, v44
	v_fmac_f32_e32 v1, v4, v45
	v_fmac_f32_e32 v2, v4, v46
	v_fmac_f32_e32 v3, v4, v47
	v_mov_b32_e32 v4, s62
	v_mul_f32_e32 v4, s46, v4
	v_fmac_f32_e32 v0, v4, v48
	v_fmac_f32_e32 v1, v4, v49
	v_fmac_f32_e32 v2, v4, v50
	v_fmac_f32_e32 v3, v4, v51
	v_mov_b32_e32 v4, s63
	v_mul_f32_e32 v4, s47, v4
	v_fmac_f32_e32 v0, v4, v52
	v_fmac_f32_e32 v1, v4, v53
	v_fmac_f32_e32 v2, v4, v54
	v_fmac_f32_e32 v3, v4, v55
	v_mov_b32_e32 v4, s20
	v_mul_f32_e32 v4, s48, v4
	v_fmac_f32_e32 v0, v4, v56
	v_fmac_f32_e32 v1, v4, v57
	v_fmac_f32_e32 v2, v4, v58
	v_fmac_f32_e32 v3, v4, v59
	v_mov_b32_e32 v4, s21
	v_mul_f32_e32 v4, s49, v4
	v_fmac_f32_e32 v0, v4, v60
	v_fmac_f32_e32 v1, v4, v61
	v_fmac_f32_e32 v2, v4, v62
	v_fmac_f32_e32 v3, v4, v63
	v_mov_b32_e32 v4, s22
	v_mul_f32_e32 v4, s50, v4
	v_fmac_f32_e32 v0, v4, v64
	v_fmac_f32_e32 v1, v4, v65
	v_fmac_f32_e32 v2, v4, v66
	v_fmac_f32_e32 v3, v4, v67
	v_mov_b32_e32 v4, s23
	v_mul_f32_e32 v4, s51, v4
	v_fmac_f32_e32 v0, v4, v68
	v_fmac_f32_e32 v1, v4, v69
	v_fmac_f32_e32 v2, v4, v70
	v_fmac_f32_e32 v3, v4, v71
	s_load_dwordx8 s[44:51], s[98:99], 0x140
	s_load_dwordx4 s[60:63], s[100:101], 0x140
	s_load_dwordx4 s[20:23], s[100:101], 0x150
	s_waitcnt lgkmcnt(0)
	v_mov_b32_e32 v4, s60
	v_mul_f32_e32 v4, s44, v4
	v_fmac_f32_e32 v0, v4, v72
	v_fmac_f32_e32 v1, v4, v73
	v_fmac_f32_e32 v2, v4, v74
	v_fmac_f32_e32 v3, v4, v75
	v_mov_b32_e32 v4, s61
	v_mul_f32_e32 v4, s45, v4
	v_fmac_f32_e32 v0, v4, v76
	v_fmac_f32_e32 v1, v4, v77
	v_fmac_f32_e32 v2, v4, v78
	v_fmac_f32_e32 v3, v4, v79
	v_mov_b32_e32 v4, s62
	v_mul_f32_e32 v4, s46, v4
	v_fmac_f32_e32 v0, v4, v80
	v_fmac_f32_e32 v1, v4, v81
	v_fmac_f32_e32 v2, v4, v82
	v_fmac_f32_e32 v3, v4, v83
	v_mov_b32_e32 v4, s63
	v_mul_f32_e32 v4, s47, v4
	v_fmac_f32_e32 v0, v4, v84
	v_fmac_f32_e32 v1, v4, v85
	v_fmac_f32_e32 v2, v4, v86
	v_fmac_f32_e32 v3, v4, v87
	v_mov_b32_e32 v4, s20
	v_mul_f32_e32 v4, s48, v4
	v_fmac_f32_e32 v0, v4, v88
	v_fmac_f32_e32 v1, v4, v89
	v_fmac_f32_e32 v2, v4, v90
	v_fmac_f32_e32 v3, v4, v91
	v_mov_b32_e32 v4, s21
	v_mul_f32_e32 v4, s49, v4
	v_fmac_f32_e32 v0, v4, v92
	v_fmac_f32_e32 v1, v4, v93
	v_fmac_f32_e32 v2, v4, v94
	v_fmac_f32_e32 v3, v4, v95
	v_mov_b32_e32 v4, s22
	v_mul_f32_e32 v4, s50, v4
	v_fmac_f32_e32 v0, v4, v96
	v_fmac_f32_e32 v1, v4, v97
	v_fmac_f32_e32 v2, v4, v98
	v_fmac_f32_e32 v3, v4, v99
	v_mov_b32_e32 v4, s23
	v_mul_f32_e32 v4, s51, v4
	v_fmac_f32_e32 v0, v4, v100
	v_fmac_f32_e32 v1, v4, v101
	v_fmac_f32_e32 v2, v4, v102
	v_fmac_f32_e32 v3, v4, v103
	s_load_dwordx8 s[44:51], s[98:99], 0x160
	s_load_dwordx4 s[60:63], s[100:101], 0x160
	s_load_dwordx4 s[20:23], s[100:101], 0x170
	s_waitcnt lgkmcnt(0)
	v_mov_b32_e32 v4, s60
	v_mul_f32_e32 v4, s44, v4
	v_fmac_f32_e32 v0, v4, v104
	v_fmac_f32_e32 v1, v4, v105
	v_fmac_f32_e32 v2, v4, v106
	v_fmac_f32_e32 v3, v4, v107
	v_mov_b32_e32 v4, s61
	v_mul_f32_e32 v4, s45, v4
	v_fmac_f32_e32 v0, v4, v108
	v_fmac_f32_e32 v1, v4, v109
	v_fmac_f32_e32 v2, v4, v110
	v_fmac_f32_e32 v3, v4, v111
	v_mov_b32_e32 v4, s62
	v_mul_f32_e32 v4, s46, v4
	v_fmac_f32_e32 v0, v4, v112
	v_fmac_f32_e32 v1, v4, v113
	v_fmac_f32_e32 v2, v4, v114
	v_fmac_f32_e32 v3, v4, v115
	v_mov_b32_e32 v4, s63
	v_mul_f32_e32 v4, s47, v4
	v_fmac_f32_e32 v0, v4, v116
	v_fmac_f32_e32 v1, v4, v117
	v_fmac_f32_e32 v2, v4, v118
	v_fmac_f32_e32 v3, v4, v119
	v_mov_b32_e32 v4, s20
	v_mul_f32_e32 v4, s48, v4
	v_fmac_f32_e32 v0, v4, v120
	v_fmac_f32_e32 v1, v4, v121
	v_fmac_f32_e32 v2, v4, v122
	v_fmac_f32_e32 v3, v4, v123
	v_mov_b32_e32 v4, s21
	v_mul_f32_e32 v4, s49, v4
	v_fmac_f32_e32 v0, v4, v124
	v_fmac_f32_e32 v1, v4, v125
	v_fmac_f32_e32 v2, v4, v126
	v_fmac_f32_e32 v3, v4, v127
	v_mov_b32_e32 v4, s22
	v_mul_f32_e32 v4, s50, v4
	v_fmac_f32_e32 v0, v4, v128
	v_fmac_f32_e32 v1, v4, v129
	v_fmac_f32_e32 v2, v4, v130
	v_fmac_f32_e32 v3, v4, v131
	v_mov_b32_e32 v4, s23
	v_mul_f32_e32 v4, s51, v4
	v_fmac_f32_e32 v0, v4, v132
	v_fmac_f32_e32 v1, v4, v133
	v_fmac_f32_e32 v2, v4, v134
	v_fmac_f32_e32 v3, v4, v135
	s_add_u32 s4, s18, 0x60000
	s_addc_u32 s5, s19, 0
	global_load_dwordx4 v[8:11], v6, s[4:5]
	s_add_u32 s4, s18, 0x61000
	s_addc_u32 s5, s19, 0
	global_load_dwordx4 v[12:15], v6, s[4:5]
	s_add_u32 s4, s18, 0x62000
	s_addc_u32 s5, s19, 0
	global_load_dwordx4 v[16:19], v6, s[4:5]
	s_add_u32 s4, s18, 0x63000
	s_addc_u32 s5, s19, 0
	global_load_dwordx4 v[20:23], v6, s[4:5]
	s_add_u32 s4, s18, 0x64000
	s_addc_u32 s5, s19, 0
	global_load_dwordx4 v[24:27], v6, s[4:5]
	s_add_u32 s4, s18, 0x65000
	s_addc_u32 s5, s19, 0
	global_load_dwordx4 v[28:31], v6, s[4:5]
	s_add_u32 s4, s18, 0x66000
	s_addc_u32 s5, s19, 0
	global_load_dwordx4 v[32:35], v6, s[4:5]
	s_add_u32 s4, s18, 0x67000
	s_addc_u32 s5, s19, 0
	global_load_dwordx4 v[36:39], v6, s[4:5]
	s_add_u32 s4, s18, 0x68000
	s_addc_u32 s5, s19, 0
	global_load_dwordx4 v[40:43], v6, s[4:5]
	s_add_u32 s4, s18, 0x69000
	s_addc_u32 s5, s19, 0
	global_load_dwordx4 v[44:47], v6, s[4:5]
	s_add_u32 s4, s18, 0x6a000
	s_addc_u32 s5, s19, 0
	global_load_dwordx4 v[48:51], v6, s[4:5]
	s_add_u32 s4, s18, 0x6b000
	s_addc_u32 s5, s19, 0
	global_load_dwordx4 v[52:55], v6, s[4:5]
	s_add_u32 s4, s18, 0x6c000
	s_addc_u32 s5, s19, 0
	global_load_dwordx4 v[56:59], v6, s[4:5]
	s_add_u32 s4, s18, 0x6d000
	s_addc_u32 s5, s19, 0
	global_load_dwordx4 v[60:63], v6, s[4:5]
	s_add_u32 s4, s18, 0x6e000
	s_addc_u32 s5, s19, 0
	global_load_dwordx4 v[64:67], v6, s[4:5]
	s_add_u32 s4, s18, 0x6f000
; __global__ void __launch_bounds__(512, 2) fwd_mega(Args a) {
;     ...
;           for (int w = gw; w < 1024 * 8; w += NGW) { const int n = w & 1023, gc = (w >> 10) * 64 + lane, g = gc >> 7;
;               float acc = 0.f;
;               for (int d = 0; d < 128; ++d) acc += pw[(size_t)gc * 128 + d] * psc[g * 128 + d] * wbp[(size_t)(g * 128 + d) * 1024 + n];
	s_addc_u32 s5, s19, 0
	global_load_dwordx4 v[68:71], v6, s[4:5]
	s_add_u32 s4, s18, 0x70000
	s_addc_u32 s5, s19, 0
	global_load_dwordx4 v[72:75], v6, s[4:5]
	s_add_u32 s4, s18, 0x71000
	s_addc_u32 s5, s19, 0
	global_load_dwordx4 v[76:79], v6, s[4:5]
	s_add_u32 s4, s18, 0x72000
	s_addc_u32 s5, s19, 0
	global_load_dwordx4 v[80:83], v6, s[4:5]
	s_add_u32 s4, s18, 0x73000
	s_addc_u32 s5, s19, 0
	global_load_dwordx4 v[84:87], v6, s[4:5]
	s_add_u32 s4, s18, 0x74000
	s_addc_u32 s5, s19, 0
	global_load_dwordx4 v[88:91], v6, s[4:5]
	s_add_u32 s4, s18, 0x75000
	s_addc_u32 s5, s19, 0
	global_load_dwordx4 v[92:95], v6, s[4:5]
	s_add_u32 s4, s18, 0x76000
	s_addc_u32 s5, s19, 0
	global_load_dwordx4 v[96:99], v6, s[4:5]
	s_add_u32 s4, s18, 0x77000
	s_addc_u32 s5, s19, 0
	global_load_dwordx4 v[100:103], v6, s[4:5]
	s_add_u32 s4, s18, 0x78000
	s_addc_u32 s5, s19, 0
	global_load_dwordx4 v[104:107], v6, s[4:5]
	s_add_u32 s4, s18, 0x79000
	s_addc_u32 s5, s19, 0
	global_load_dwordx4 v[108:111], v6, s[4:5]
	s_add_u32 s4, s18, 0x7a000
	s_addc_u32 s5, s19, 0
	global_load_dwordx4 v[112:115], v6, s[4:5]
	s_add_u32 s4, s18, 0x7b000
	s_addc_u32 s5, s19, 0
	global_load_dwordx4 v[116:119], v6, s[4:5]
	s_add_u32 s4, s18, 0x7c000
	s_addc_u32 s5, s19, 0
	global_load_dwordx4 v[120:123], v6, s[4:5]
	s_add_u32 s4, s18, 0x7d000
	s_addc_u32 s5, s19, 0
	global_load_dwordx4 v[124:127], v6, s[4:5]
	s_add_u32 s4, s18, 0x7e000
	s_addc_u32 s5, s19, 0
	global_load_dwordx4 v[128:131], v6, s[4:5]
	s_add_u32 s4, s18, 0x7f000
	s_addc_u32 s5, s19, 0
	global_load_dwordx4 v[132:135], v6, s[4:5]
	s_load_dwordx8 s[44:51], s[98:99], 0x180
	s_load_dwordx4 s[60:63], s[100:101], 0x180
	s_load_dwordx4 s[20:23], s[100:101], 0x190
	s_waitcnt vmcnt(0) lgkmcnt(0)
	v_mov_b32_e32 v4, s60
	v_mul_f32_e32 v4, s44, v4
	v_fmac_f32_e32 v0, v4, v8
	v_fmac_f32_e32 v1, v4, v9
	v_fmac_f32_e32 v2, v4, v10
	v_fmac_f32_e32 v3, v4, v11
	v_mov_b32_e32 v4, s61
	v_mul_f32_e32 v4, s45, v4
	v_fmac_f32_e32 v0, v4, v12
	v_fmac_f32_e32 v1, v4, v13
	v_fmac_f32_e32 v2, v4, v14
	v_fmac_f32_e32 v3, v4, v15
	v_mov_b32_e32 v4, s62
	v_mul_f32_e32 v4, s46, v4
	v_fmac_f32_e32 v0, v4, v16
	v_fmac_f32_e32 v1, v4, v17
	v_fmac_f32_e32 v2, v4, v18
	v_fmac_f32_e32 v3, v4, v19
	v_mov_b32_e32 v4, s63
	v_mul_f32_e32 v4, s47, v4
	v_fmac_f32_e32 v0, v4, v20
	v_fmac_f32_e32 v1, v4, v21
	v_fmac_f32_e32 v2, v4, v22
	v_fmac_f32_e32 v3, v4, v23
	v_mov_b32_e32 v4, s20
	v_mul_f32_e32 v4, s48, v4
	v_fmac_f32_e32 v0, v4, v24
	v_fmac_f32_e32 v1, v4, v25
	v_fmac_f32_e32 v2, v4, v26
	v_fmac_f32_e32 v3, v4, v27
	v_mov_b32_e32 v4, s21
	v_mul_f32_e32 v4, s49, v4
	v_fmac_f32_e32 v0, v4, v28
	v_fmac_f32_e32 v1, v4, v29
	v_fmac_f32_e32 v2, v4, v30
	v_fmac_f32_e32 v3, v4, v31
	v_mov_b32_e32 v4, s22
	v_mul_f32_e32 v4, s50, v4
	v_fmac_f32_e32 v0, v4, v32
	v_fmac_f32_e32 v1, v4, v33
	v_fmac_f32_e32 v2, v4, v34
	v_fmac_f32_e32 v3, v4, v35
	v_mov_b32_e32 v4, s23
	v_mul_f32_e32 v4, s51, v4
	v_fmac_f32_e32 v0, v4, v36
	v_fmac_f32_e32 v1, v4, v37
	v_fmac_f32_e32 v2, v4, v38
	v_fmac_f32_e32 v3, v4, v39
	s_load_dwordx8 s[44:51], s[98:99], 0x1a0
	s_load_dwordx4 s[60:63], s[100:101], 0x1a0
	s_load_dwordx4 s[20:23], s[100:101], 0x1b0
	s_waitcnt lgkmcnt(0)
	v_mov_b32_e32 v4, s60
	v_mul_f32_e32 v4, s44, v4
	v_fmac_f32_e32 v0, v4, v40
	v_fmac_f32_e32 v1, v4, v41
	v_fmac_f32_e32 v2, v4, v42
	v_fmac_f32_e32 v3, v4, v43
	v_mov_b32_e32 v4, s61
	v_mul_f32_e32 v4, s45, v4
	v_fmac_f32_e32 v0, v4, v44
	v_fmac_f32_e32 v1, v4, v45
	v_fmac_f32_e32 v2, v4, v46
	v_fmac_f32_e32 v3, v4, v47
	v_mov_b32_e32 v4, s62
	v_mul_f32_e32 v4, s46, v4
	v_fmac_f32_e32 v0, v4, v48
	v_fmac_f32_e32 v1, v4, v49
	v_fmac_f32_e32 v2, v4, v50
	v_fmac_f32_e32 v3, v4, v51
	v_mov_b32_e32 v4, s63
	v_mul_f32_e32 v4, s47, v4
	v_fmac_f32_e32 v0, v4, v52
	v_fmac_f32_e32 v1, v4, v53
	v_fmac_f32_e32 v2, v4, v54
	v_fmac_f32_e32 v3, v4, v55
	v_mov_b32_e32 v4, s20
	v_mul_f32_e32 v4, s48, v4
	v_fmac_f32_e32 v0, v4, v56
	v_fmac_f32_e32 v1, v4, v57
	v_fmac_f32_e32 v2, v4, v58
	v_fmac_f32_e32 v3, v4, v59
	v_mov_b32_e32 v4, s21
	v_mul_f32_e32 v4, s49, v4
	v_fmac_f32_e32 v0, v4, v60
	v_fmac_f32_e32 v1, v4, v61
	v_fmac_f32_e32 v2, v4, v62
	v_fmac_f32_e32 v3, v4, v63
	v_mov_b32_e32 v4, s22
	v_mul_f32_e32 v4, s50, v4
	v_fmac_f32_e32 v0, v4, v64
	v_fmac_f32_e32 v1, v4, v65
	v_fmac_f32_e32 v2, v4, v66
	v_fmac_f32_e32 v3, v4, v67
	v_mov_b32_e32 v4, s23
	v_mul_f32_e32 v4, s51, v4
	v_fmac_f32_e32 v0, v4, v68
	v_fmac_f32_e32 v1, v4, v69
	v_fmac_f32_e32 v2, v4, v70
	v_fmac_f32_e32 v3, v4, v71
	s_load_dwordx8 s[44:51], s[98:99], 0x1c0
	s_load_dwordx4 s[60:63], s[100:101], 0x1c0
	s_load_dwordx4 s[20:23], s[100:101], 0x1d0
	s_waitcnt lgkmcnt(0)
; __device__ __forceinline__ unsigned f2bf(float f) { unsigned u = __builtin_bit_cast(unsigned, f); return (u + 0x7fffu + ((u >> 16) & 1u)) >> 16; }
; __global__ void __launch_bounds__(512, 2) fwd_mega(Args a) {
;     ...
;               for (int d = 0; d < 128; ++d) acc += pw[(size_t)gc * 128 + d] * psc[g * 128 + d] * wbp[(size_t)(g * 128 + d) * 1024 + n];
;               Wba[(size_t)n * 1024 + 512 + gc] = (bf16)f2bf(acc); } }
	v_mov_b32_e32 v4, s60
	v_mul_f32_e32 v4, s44, v4
	v_fmac_f32_e32 v0, v4, v72
	v_fmac_f32_e32 v1, v4, v73
	v_fmac_f32_e32 v2, v4, v74
	v_fmac_f32_e32 v3, v4, v75
	v_mov_b32_e32 v4, s61
	v_mul_f32_e32 v4, s45, v4
	v_fmac_f32_e32 v0, v4, v76
	v_fmac_f32_e32 v1, v4, v77
	v_fmac_f32_e32 v2, v4, v78
	v_fmac_f32_e32 v3, v4, v79
	v_mov_b32_e32 v4, s62
	v_mul_f32_e32 v4, s46, v4
	v_fmac_f32_e32 v0, v4, v80
	v_fmac_f32_e32 v1, v4, v81
	v_fmac_f32_e32 v2, v4, v82
	v_fmac_f32_e32 v3, v4, v83
	v_mov_b32_e32 v4, s63
	v_mul_f32_e32 v4, s47, v4
	v_fmac_f32_e32 v0, v4, v84
	v_fmac_f32_e32 v1, v4, v85
	v_fmac_f32_e32 v2, v4, v86
	v_fmac_f32_e32 v3, v4, v87
	v_mov_b32_e32 v4, s20
	v_mul_f32_e32 v4, s48, v4
	v_fmac_f32_e32 v0, v4, v88
	v_fmac_f32_e32 v1, v4, v89
	v_fmac_f32_e32 v2, v4, v90
	v_fmac_f32_e32 v3, v4, v91
	v_mov_b32_e32 v4, s21
	v_mul_f32_e32 v4, s49, v4
	v_fmac_f32_e32 v0, v4, v92
	v_fmac_f32_e32 v1, v4, v93
	v_fmac_f32_e32 v2, v4, v94
	v_fmac_f32_e32 v3, v4, v95
	v_mov_b32_e32 v4, s22
	v_mul_f32_e32 v4, s50, v4
	v_fmac_f32_e32 v0, v4, v96
	v_fmac_f32_e32 v1, v4, v97
	v_fmac_f32_e32 v2, v4, v98
	v_fmac_f32_e32 v3, v4, v99
	v_mov_b32_e32 v4, s23
	v_mul_f32_e32 v4, s51, v4
	v_fmac_f32_e32 v0, v4, v100
	v_fmac_f32_e32 v1, v4, v101
	v_fmac_f32_e32 v2, v4, v102
	v_fmac_f32_e32 v3, v4, v103
	s_load_dwordx8 s[44:51], s[98:99], 0x1e0
	s_load_dwordx4 s[60:63], s[100:101], 0x1e0
	s_load_dwordx4 s[20:23], s[100:101], 0x1f0
	s_waitcnt lgkmcnt(0)
	v_mov_b32_e32 v4, s60
	v_mul_f32_e32 v4, s44, v4
	v_fmac_f32_e32 v0, v4, v104
	v_fmac_f32_e32 v1, v4, v105
	v_fmac_f32_e32 v2, v4, v106
	v_fmac_f32_e32 v3, v4, v107
	v_mov_b32_e32 v4, s61
	v_mul_f32_e32 v4, s45, v4
	v_fmac_f32_e32 v0, v4, v108
	v_fmac_f32_e32 v1, v4, v109
	v_fmac_f32_e32 v2, v4, v110
	v_fmac_f32_e32 v3, v4, v111
	v_mov_b32_e32 v4, s62
	v_mul_f32_e32 v4, s46, v4
	v_fmac_f32_e32 v0, v4, v112
	v_fmac_f32_e32 v1, v4, v113
	v_fmac_f32_e32 v2, v4, v114
	v_fmac_f32_e32 v3, v4, v115
	v_mov_b32_e32 v4, s63
	v_mul_f32_e32 v4, s47, v4
	v_fmac_f32_e32 v0, v4, v116
	v_fmac_f32_e32 v1, v4, v117
	v_fmac_f32_e32 v2, v4, v118
	v_fmac_f32_e32 v3, v4, v119
	v_mov_b32_e32 v4, s20
	v_mul_f32_e32 v4, s48, v4
	v_fmac_f32_e32 v0, v4, v120
	v_fmac_f32_e32 v1, v4, v121
	v_fmac_f32_e32 v2, v4, v122
	v_fmac_f32_e32 v3, v4, v123
	v_mov_b32_e32 v4, s21
	v_mul_f32_e32 v4, s49, v4
	v_fmac_f32_e32 v0, v4, v124
	v_fmac_f32_e32 v1, v4, v125
	v_fmac_f32_e32 v2, v4, v126
	v_fmac_f32_e32 v3, v4, v127
	v_mov_b32_e32 v4, s22
	v_mul_f32_e32 v4, s50, v4
	v_fmac_f32_e32 v0, v4, v128
	v_fmac_f32_e32 v1, v4, v129
	v_fmac_f32_e32 v2, v4, v130
	v_fmac_f32_e32 v3, v4, v131
	v_mov_b32_e32 v4, s23
	v_mul_f32_e32 v4, s51, v4
	v_fmac_f32_e32 v0, v4, v132
	v_fmac_f32_e32 v1, v4, v133
	v_fmac_f32_e32 v2, v4, v134
	v_fmac_f32_e32 v3, v4, v135
	s_movk_i32 s5, 0x7fff
	v_lshlrev_b32_e32 v137, 2, v203
	v_lshl_or_b32 v136, s1, 8, v137
	v_mov_b32_e32 v137, 0
	v_lshlrev_b64 v[136:137], 11, v[136:137]
	s_lshl_b32 s4, s0, 1
	s_add_u32 s20, s76, s4
	s_addc_u32 s21, s77, 0
	v_lshl_add_u64 v[136:137], v[136:137], 0, s[20:21]
	s_mov_b64 s[20:21], 0x800
	v_bfe_u32 v5, v0, 16, 1
	v_add3_u32 v5, v0, v5, s5
	global_store_short_d16_hi v[136:137], v5, off offset:1024
	v_lshl_add_u64 v[136:137], v[136:137], 0, s[20:21]
	s_nop 0
	v_bfe_u32 v5, v1, 16, 1
	v_add3_u32 v5, v1, v5, s5
	global_store_short_d16_hi v[136:137], v5, off offset:1024
	v_lshl_add_u64 v[136:137], v[136:137], 0, s[20:21]
	s_nop 0
	v_bfe_u32 v5, v2, 16, 1
	v_add3_u32 v5, v2, v5, s5
	global_store_short_d16_hi v[136:137], v5, off offset:1024
	v_lshl_add_u64 v[136:137], v[136:137], 0, s[20:21]
	s_nop 0
	v_bfe_u32 v5, v3, 16, 1
	v_add3_u32 v5, v3, v5, s5
	global_store_short_d16_hi v[136:137], v5, off offset:1024
	s_add_i32 s8, s8, s9
	s_cmpk_gt_i32 s8, 0x7ff
	s_cbranch_scc0 .Lfold_item

; __global__ void __launch_bounds__(512, 2) fwd_mega(Args a) {
	.amdhsa_kernel _Z8fwd_mega4Args
		.amdhsa_group_segment_fixed_size 0
		.amdhsa_private_segment_fixed_size 0
		.amdhsa_kernarg_size 480
		.amdhsa_user_sgpr_count 2
		.amdhsa_user_sgpr_dispatch_ptr 0
		.amdhsa_user_sgpr_queue_ptr 0
		.amdhsa_user_sgpr_kernarg_segment_ptr 1
		.amdhsa_user_sgpr_dispatch_id 0
		.amdhsa_user_sgpr_kernarg_preload_length 0
		.amdhsa_user_sgpr_kernarg_preload_offset 0
		.amdhsa_user_sgpr_private_segment_size 0
		.amdhsa_uses_dynamic_stack 0
		.amdhsa_enable_private_segment 0
		.amdhsa_system_sgpr_workgroup_id_x 1
		.amdhsa_system_sgpr_workgroup_id_y 0
		.amdhsa_system_sgpr_workgroup_id_z 0
		.amdhsa_system_sgpr_workgroup_info 0
		.amdhsa_system_vgpr_workitem_id 2
		.amdhsa_next_free_vgpr 248
		.amdhsa_next_free_sgpr 102
		.amdhsa_accum_offset 248
		.amdhsa_reserve_vcc 1
		.amdhsa_float_round_mode_32 0
		.amdhsa_float_round_mode_16_64 0
		.amdhsa_float_denorm_mode_32 3
		.amdhsa_float_denorm_mode_16_64 3
		.amdhsa_dx10_clamp 1
		.amdhsa_ieee_mode 1
		.amdhsa_fp16_overflow 0
		.amdhsa_tg_split 0
		.amdhsa_exception_fp_ieee_invalid_op 0
		.amdhsa_exception_fp_denorm_src 0
		.amdhsa_exception_fp_ieee_div_zero 0
		.amdhsa_exception_fp_ieee_overflow 0
		.amdhsa_exception_fp_ieee_underflow 0
		.amdhsa_exception_fp_ieee_inexact 0
		.amdhsa_exception_int_div_zero 0
	.end_amdhsa_kernel

; __global__ void __launch_bounds__(512, 2) fwd_mega(Args a) {
.Lfunc_end0:
	.size	_Z8fwd_mega4Args, .Lfunc_end0-_Z8fwd_mega4Args
	.set _Z8fwd_mega4Args.num_vgpr, 248
	.set _Z8fwd_mega4Args.num_agpr, 0
	.set _Z8fwd_mega4Args.numbered_sgpr, 102
	.set _Z8fwd_mega4Args.num_named_barrier, 0
	.set _Z8fwd_mega4Args.private_seg_size, 0
	.set _Z8fwd_mega4Args.uses_vcc, 1
	.set _Z8fwd_mega4Args.uses_flat_scratch, 0
	.set _Z8fwd_mega4Args.has_dyn_sized_stack, 0
	.set _Z8fwd_mega4Args.has_recursion, 0
	.set _Z8fwd_mega4Args.has_indirect_call, 0

; __global__ void __launch_bounds__(512, 2) fwd_mega(Args a) {
amdhsa.kernels:
  - .agpr_count:     0
    .args:
      - .offset:         0
        .size:           224
        .value_kind:     by_value
      - .offset:         224
        .size:           4
        .value_kind:     hidden_block_count_x
      - .offset:         228
        .size:           4
        .value_kind:     hidden_block_count_y
      - .offset:         232
        .size:           4
        .value_kind:     hidden_block_count_z
      - .offset:         236
        .size:           2
        .value_kind:     hidden_group_size_x
      - .offset:         238
        .size:           2
        .value_kind:     hidden_group_size_y
      - .offset:         240
        .size:           2
        .value_kind:     hidden_group_size_z
      - .offset:         242
        .size:           2
        .value_kind:     hidden_remainder_x
      - .offset:         244
        .size:           2
        .value_kind:     hidden_remainder_y
      - .offset:         246
        .size:           2
        .value_kind:     hidden_remainder_z
      - .offset:         264
        .size:           8
        .value_kind:     hidden_global_offset_x
      - .offset:         272
        .size:           8
        .value_kind:     hidden_global_offset_y
      - .offset:         280
        .size:           8
        .value_kind:     hidden_global_offset_z
      - .offset:         288
        .size:           2
        .value_kind:     hidden_grid_dims
      - .offset:         312
        .size:           8
        .value_kind:     hidden_multigrid_sync_arg
      - .offset:         344
        .size:           4
        .value_kind:     hidden_dynamic_lds_size
    .group_segment_fixed_size: 0
    .kernarg_segment_align: 8
    .kernarg_segment_size: 480
    .language:       OpenCL C
    .language_version:
      - 2
      - 0
    .max_flat_workgroup_size: 512
    .name:           _Z8fwd_mega4Args
    .private_segment_fixed_size: 0
    .sgpr_count:     108
    .sgpr_spill_count: 14
    .symbol:         _Z8fwd_mega4Args.kd
    .uniform_work_group_size: 1
    .uses_dynamic_stack: false
    .vgpr_count:     248
    .vgpr_spill_count: 0
    .wavefront_size: 64
